# gla_b loop: full drain vmcnt(0) replaced by counted wait vmcnt(16) so chunks are consumed as they arrive
# baseline (speedup 1.0000x reference)
; __device__ __forceinline__ unsigned pack2(float lo, float hi) { const f32x2_t v = {lo, hi}; const bf16x2_t b = __builtin_convertvector(v, bf16x2_t); return __builtin_bit_cast(unsigned, b); }
; __device__ __forceinline__ float bflo(unsigned w) { return __uint_as_float(w << 16); }
; __device__ __forceinline__ float bfhi(unsigned w) { return __uint_as_float(w & 0xffff0000u); }
; __device__ void phase_gla_b(CP P) {
;     ...
;         bf16_t* base = GST + ((size_t)bhd * 128) * 8192 + e; const float* dbase = GDEC + ((size_t)bhd * 128) * 64 + d;
; #pragma unroll 1
;         for (int c0 = 0; c0 < 128; c0 += 8) { uint4 t[8]; float dc[8];
; #pragma unroll
;             for (int k = 0; k < 8; ++k) { const int c = dir == 0 ? c0 + k : 127 - (c0 + k); t[k] = *(const uint4*)(base + (size_t)c * 8192); dc[k] = dbase[(size_t)c * 64]; }
; #pragma unroll
;             for (int k = 0; k < 8; ++k) { const int c = dir == 0 ? c0 + k : 127 - (c0 + k);
;                 uint4 o; o.x = pack2(S0[0], S0[1]); o.y = pack2(S0[2], S0[3]); o.z = pack2(S1[0], S1[1]); o.w = pack2(S1[2], S1[3]); *(uint4*)(base + (size_t)c * 8192) = o;
;                 S0 = dc[k] * S0 + (f32x4){bflo(t[k].x), bfhi(t[k].x), bflo(t[k].y), bfhi(t[k].y)}; S1 = dc[k] * S1 + (f32x4){bflo(t[k].z), bfhi(t[k].z), bflo(t[k].w), bfhi(t[k].w)}; } }
.LBB0_163:
	s_add_i32 s13, s12, 7
	v_mov_b32_e32 v0, s13
	v_mov_b32_e32 v1, s11
	v_cndmask_b32_e32 v72, v0, v1, vcc
	v_mov_b32_e32 v73, v184
	v_lshlrev_b64 v[0:1], 14, v[72:73]
	v_lshl_add_u64 v[0:1], v[32:33], 0, v[0:1]
	global_load_dwordx4 v[28:31], v[0:1], off
	v_lshlrev_b64 v[0:1], 8, v[72:73]
	v_lshl_add_u64 v[0:1], v[34:35], 0, v[0:1]
	s_add_i32 s13, s12, 6
	s_add_i32 s16, s11, 1
	global_load_dword v70, v[0:1], off
	v_mov_b32_e32 v0, s13
	v_mov_b32_e32 v1, s16
	v_cndmask_b32_e32 v74, v0, v1, vcc
	v_mov_b32_e32 v75, v184
	v_lshlrev_b64 v[0:1], 14, v[74:75]
	v_lshl_add_u64 v[0:1], v[32:33], 0, v[0:1]
	global_load_dwordx4 v[24:27], v[0:1], off
	v_lshlrev_b64 v[0:1], 8, v[74:75]
	v_lshl_add_u64 v[0:1], v[34:35], 0, v[0:1]
	s_add_i32 s13, s12, 5
	s_add_i32 s16, s11, 2
	global_load_dword v66, v[0:1], off
	v_mov_b32_e32 v0, s13
	v_mov_b32_e32 v1, s16
	v_cndmask_b32_e32 v68, v0, v1, vcc
	v_mov_b32_e32 v69, v184
	v_lshlrev_b64 v[0:1], 14, v[68:69]
	v_lshl_add_u64 v[0:1], v[32:33], 0, v[0:1]
	global_load_dwordx4 v[20:23], v[0:1], off
	v_lshlrev_b64 v[0:1], 8, v[68:69]
	v_lshl_add_u64 v[0:1], v[34:35], 0, v[0:1]
	s_add_i32 s13, s12, 4
	s_add_i32 s16, s11, 3
	global_load_dword v62, v[0:1], off
	v_mov_b32_e32 v0, s13
	v_mov_b32_e32 v1, s16
	v_cndmask_b32_e32 v64, v0, v1, vcc
	v_mov_b32_e32 v65, v184
	v_lshlrev_b64 v[0:1], 14, v[64:65]
	v_lshl_add_u64 v[0:1], v[32:33], 0, v[0:1]
	global_load_dwordx4 v[16:19], v[0:1], off
	v_lshlrev_b64 v[0:1], 8, v[64:65]
	v_lshl_add_u64 v[0:1], v[34:35], 0, v[0:1]
	s_add_i32 s13, s12, 3
	s_add_i32 s16, s11, 4
	global_load_dword v58, v[0:1], off
	v_mov_b32_e32 v0, s13
	v_mov_b32_e32 v1, s16
	v_cndmask_b32_e32 v60, v0, v1, vcc
	v_mov_b32_e32 v61, v184
	v_lshlrev_b64 v[0:1], 14, v[60:61]
	v_lshl_add_u64 v[0:1], v[32:33], 0, v[0:1]
	global_load_dwordx4 v[12:15], v[0:1], off
	v_lshlrev_b64 v[0:1], 8, v[60:61]
	v_lshl_add_u64 v[0:1], v[34:35], 0, v[0:1]
	s_add_i32 s13, s12, 2
	s_add_i32 s16, s11, 5
	global_load_dword v54, v[0:1], off
	v_mov_b32_e32 v0, s13
	v_mov_b32_e32 v1, s16
	v_cndmask_b32_e32 v56, v0, v1, vcc
	v_mov_b32_e32 v57, v184
	v_lshlrev_b64 v[0:1], 14, v[56:57]
	v_lshl_add_u64 v[0:1], v[32:33], 0, v[0:1]
	global_load_dwordx4 v[8:11], v[0:1], off
	v_lshlrev_b64 v[0:1], 8, v[56:57]
	v_lshl_add_u64 v[0:1], v[34:35], 0, v[0:1]
	s_add_i32 s13, s12, 1
	s_add_i32 s16, s11, 6
	global_load_dword v50, v[0:1], off
	v_mov_b32_e32 v0, s13
	v_mov_b32_e32 v1, s16
	v_cndmask_b32_e32 v52, v0, v1, vcc
	v_mov_b32_e32 v53, v184
	v_lshlrev_b64 v[0:1], 14, v[52:53]
	v_lshl_add_u64 v[0:1], v[32:33], 0, v[0:1]
	global_load_dwordx4 v[4:7], v[0:1], off
	v_lshlrev_b64 v[0:1], 8, v[52:53]
	v_lshl_add_u64 v[0:1], v[34:35], 0, v[0:1]
	s_add_i32 s13, s11, 7
	global_load_dword v46, v[0:1], off
	v_mov_b32_e32 v0, s12
	v_mov_b32_e32 v1, s13
	v_cndmask_b32_e32 v48, v0, v1, vcc
	v_mov_b32_e32 v49, v184
	v_lshlrev_b64 v[0:1], 14, v[48:49]
	v_lshl_add_u64 v[0:1], v[32:33], 0, v[0:1]
	v_lshlrev_b64 v[76:77], 8, v[48:49]
	global_load_dwordx4 v[0:3], v[0:1], off
	v_lshl_add_u64 v[76:77], v[34:35], 0, v[76:77]
	global_load_dword v44, v[76:77], off
	v_lshlrev_b32_e32 v72, 14, v72
	v_cvt_pk_bf16_f32 v76, v36, v37
	v_cvt_pk_bf16_f32 v77, v38, v39
	v_cvt_pk_bf16_f32 v78, v40, v41
	v_cvt_pk_bf16_f32 v79, v42, v43
	v_lshl_add_u64 v[72:73], v[32:33], 0, v[72:73]
	global_store_dwordx4 v[72:73], v[76:79], off
	s_waitcnt vmcnt(16)
	v_lshlrev_b32_e32 v72, 16, v28
	v_and_b32_e32 v73, 0xffff0000, v28
	v_lshlrev_b32_e32 v28, 16, v29
	v_and_b32_e32 v29, 0xffff0000, v29
	s_waitcnt vmcnt(15)
	v_pk_fma_f32 v[38:39], v[38:39], v[70:71], v[28:29] op_sel_hi:[1,0,1]
	v_lshlrev_b32_e32 v28, 16, v30
	v_and_b32_e32 v29, 0xffff0000, v30
	v_lshlrev_b32_e32 v30, 16, v31
	v_and_b32_e32 v31, 0xffff0000, v31
	v_pk_fma_f32 v[36:37], v[36:37], v[70:71], v[72:73] op_sel_hi:[1,0,1]
	v_pk_fma_f32 v[42:43], v[42:43], v[70:71], v[30:31] op_sel_hi:[1,0,1]
	v_pk_fma_f32 v[40:41], v[40:41], v[70:71], v[28:29] op_sel_hi:[1,0,1]
	v_lshlrev_b32_e32 v70, 14, v74
	v_mov_b32_e32 v71, v184
	v_cvt_pk_bf16_f32 v28, v36, v37
	v_cvt_pk_bf16_f32 v29, v38, v39
	v_cvt_pk_bf16_f32 v30, v40, v41
	v_cvt_pk_bf16_f32 v31, v42, v43
	v_lshl_add_u64 v[70:71], v[32:33], 0, v[70:71]
	global_store_dwordx4 v[70:71], v[28:31], off
	s_add_i32 s12, s12, -8
	s_add_i32 s13, s11, 8
	s_waitcnt vmcnt(15)
	v_lshlrev_b32_e32 v28, 16, v24
	v_and_b32_e32 v29, 0xffff0000, v24
	v_lshlrev_b32_e32 v24, 16, v25
	v_and_b32_e32 v25, 0xffff0000, v25
	s_waitcnt vmcnt(14)
	v_pk_fma_f32 v[30:31], v[38:39], v[66:67], v[24:25] op_sel_hi:[1,0,1]
	v_lshlrev_b32_e32 v24, 16, v26
	v_and_b32_e32 v25, 0xffff0000, v26
	v_lshlrev_b32_e32 v26, 16, v27
	v_and_b32_e32 v27, 0xffff0000, v27
	v_pk_fma_f32 v[28:29], v[36:37], v[66:67], v[28:29] op_sel_hi:[1,0,1]
	v_pk_fma_f32 v[36:37], v[42:43], v[66:67], v[26:27] op_sel_hi:[1,0,1]
	v_pk_fma_f32 v[38:39], v[40:41], v[66:67], v[24:25] op_sel_hi:[1,0,1]
	v_lshlrev_b32_e32 v40, 14, v68
	v_mov_b32_e32 v41, v184
	v_cvt_pk_bf16_f32 v24, v28, v29
	v_cvt_pk_bf16_f32 v25, v30, v31
	v_cvt_pk_bf16_f32 v26, v38, v39
	v_cvt_pk_bf16_f32 v27, v36, v37
	v_lshl_add_u64 v[40:41], v[32:33], 0, v[40:41]
	global_store_dwordx4 v[40:41], v[24:27], off
	s_cmpk_gt_u32 s11, 0x77
	s_mov_b32 s11, s13
	s_waitcnt vmcnt(14)
; __device__ __forceinline__ unsigned pack2(float lo, float hi) { const f32x2_t v = {lo, hi}; const bf16x2_t b = __builtin_convertvector(v, bf16x2_t); return __builtin_bit_cast(unsigned, b); }
; __device__ __forceinline__ float bflo(unsigned w) { return __uint_as_float(w << 16); }
; __device__ __forceinline__ float bfhi(unsigned w) { return __uint_as_float(w & 0xffff0000u); }
; __device__ void phase_gla_b(CP P) {
;     ...
;             for (int k = 0; k < 8; ++k) { const int c = dir == 0 ? c0 + k : 127 - (c0 + k); t[k] = *(const uint4*)(base + (size_t)c * 8192); dc[k] = dbase[(size_t)c * 64]; }
; #pragma unroll
;             for (int k = 0; k < 8; ++k) { const int c = dir == 0 ? c0 + k : 127 - (c0 + k);
;                 uint4 o; o.x = pack2(S0[0], S0[1]); o.y = pack2(S0[2], S0[3]); o.z = pack2(S1[0], S1[1]); o.w = pack2(S1[2], S1[3]); *(uint4*)(base + (size_t)c * 8192) = o;
;                 S0 = dc[k] * S0 + (f32x4){bflo(t[k].x), bfhi(t[k].x), bflo(t[k].y), bfhi(t[k].y)}; S1 = dc[k] * S1 + (f32x4){bflo(t[k].z), bfhi(t[k].z), bflo(t[k].w), bfhi(t[k].w)}; } }
	v_lshlrev_b32_e32 v24, 16, v20
	v_and_b32_e32 v25, 0xffff0000, v20
	v_lshlrev_b32_e32 v20, 16, v21
	v_and_b32_e32 v21, 0xffff0000, v21
	s_waitcnt vmcnt(13)
	v_pk_fma_f32 v[26:27], v[30:31], v[62:63], v[20:21] op_sel_hi:[1,0,1]
	v_lshlrev_b32_e32 v20, 16, v22
	v_and_b32_e32 v21, 0xffff0000, v22
	v_lshlrev_b32_e32 v22, 16, v23
	v_and_b32_e32 v23, 0xffff0000, v23
	v_pk_fma_f32 v[24:25], v[28:29], v[62:63], v[24:25] op_sel_hi:[1,0,1]
	v_pk_fma_f32 v[28:29], v[36:37], v[62:63], v[22:23] op_sel_hi:[1,0,1]
	v_pk_fma_f32 v[30:31], v[38:39], v[62:63], v[20:21] op_sel_hi:[1,0,1]
	v_lshlrev_b32_e32 v36, 14, v64
	v_mov_b32_e32 v37, v184
	v_cvt_pk_bf16_f32 v20, v24, v25
	v_cvt_pk_bf16_f32 v21, v26, v27
	v_cvt_pk_bf16_f32 v22, v30, v31
	v_cvt_pk_bf16_f32 v23, v28, v29
	v_lshl_add_u64 v[36:37], v[32:33], 0, v[36:37]
	global_store_dwordx4 v[36:37], v[20:23], off
	s_waitcnt vmcnt(13)
	s_nop 0
	v_lshlrev_b32_e32 v20, 16, v16
	v_and_b32_e32 v21, 0xffff0000, v16
	v_lshlrev_b32_e32 v16, 16, v17
	v_and_b32_e32 v17, 0xffff0000, v17
	s_waitcnt vmcnt(12)
	v_pk_fma_f32 v[22:23], v[26:27], v[58:59], v[16:17] op_sel_hi:[1,0,1]
	v_lshlrev_b32_e32 v16, 16, v18
	v_and_b32_e32 v17, 0xffff0000, v18
	v_lshlrev_b32_e32 v18, 16, v19
	v_and_b32_e32 v19, 0xffff0000, v19
	v_pk_fma_f32 v[20:21], v[24:25], v[58:59], v[20:21] op_sel_hi:[1,0,1]
	v_pk_fma_f32 v[24:25], v[28:29], v[58:59], v[18:19] op_sel_hi:[1,0,1]
	v_pk_fma_f32 v[26:27], v[30:31], v[58:59], v[16:17] op_sel_hi:[1,0,1]
	v_lshlrev_b32_e32 v28, 14, v60
	v_mov_b32_e32 v29, v184
	v_cvt_pk_bf16_f32 v16, v20, v21
	v_cvt_pk_bf16_f32 v17, v22, v23
	v_cvt_pk_bf16_f32 v18, v26, v27
	v_cvt_pk_bf16_f32 v19, v24, v25
	v_lshl_add_u64 v[28:29], v[32:33], 0, v[28:29]
	global_store_dwordx4 v[28:29], v[16:19], off
	s_waitcnt vmcnt(12)
	s_nop 0
	v_lshlrev_b32_e32 v16, 16, v12
	v_and_b32_e32 v17, 0xffff0000, v12
	v_lshlrev_b32_e32 v12, 16, v13
	v_and_b32_e32 v13, 0xffff0000, v13
	s_waitcnt vmcnt(11)
	v_pk_fma_f32 v[18:19], v[22:23], v[54:55], v[12:13] op_sel_hi:[1,0,1]
	v_lshlrev_b32_e32 v12, 16, v14
	v_and_b32_e32 v13, 0xffff0000, v14
	v_lshlrev_b32_e32 v14, 16, v15
	v_and_b32_e32 v15, 0xffff0000, v15
	v_pk_fma_f32 v[16:17], v[20:21], v[54:55], v[16:17] op_sel_hi:[1,0,1]
	v_pk_fma_f32 v[20:21], v[24:25], v[54:55], v[14:15] op_sel_hi:[1,0,1]
	v_pk_fma_f32 v[22:23], v[26:27], v[54:55], v[12:13] op_sel_hi:[1,0,1]
	v_lshlrev_b32_e32 v24, 14, v56
	v_mov_b32_e32 v25, v184
	v_cvt_pk_bf16_f32 v12, v16, v17
	v_cvt_pk_bf16_f32 v13, v18, v19
	v_cvt_pk_bf16_f32 v14, v22, v23
	v_cvt_pk_bf16_f32 v15, v20, v21
	v_lshl_add_u64 v[24:25], v[32:33], 0, v[24:25]
	global_store_dwordx4 v[24:25], v[12:15], off
	s_waitcnt vmcnt(11)
	s_nop 0
	v_lshlrev_b32_e32 v12, 16, v8
	v_and_b32_e32 v13, 0xffff0000, v8
	v_lshlrev_b32_e32 v8, 16, v9
	v_and_b32_e32 v9, 0xffff0000, v9
	s_waitcnt vmcnt(10)
	v_pk_fma_f32 v[14:15], v[18:19], v[50:51], v[8:9] op_sel_hi:[1,0,1]
	v_lshlrev_b32_e32 v8, 16, v10
	v_and_b32_e32 v9, 0xffff0000, v10
	v_lshlrev_b32_e32 v10, 16, v11
	v_and_b32_e32 v11, 0xffff0000, v11
	v_pk_fma_f32 v[12:13], v[16:17], v[50:51], v[12:13] op_sel_hi:[1,0,1]
	v_pk_fma_f32 v[16:17], v[20:21], v[50:51], v[10:11] op_sel_hi:[1,0,1]
	v_pk_fma_f32 v[18:19], v[22:23], v[50:51], v[8:9] op_sel_hi:[1,0,1]
	v_lshlrev_b32_e32 v20, 14, v52
	v_mov_b32_e32 v21, v184
	v_cvt_pk_bf16_f32 v8, v12, v13
	v_cvt_pk_bf16_f32 v9, v14, v15
	v_cvt_pk_bf16_f32 v10, v18, v19
	v_cvt_pk_bf16_f32 v11, v16, v17
	v_lshl_add_u64 v[20:21], v[32:33], 0, v[20:21]
	global_store_dwordx4 v[20:21], v[8:11], off
	s_waitcnt vmcnt(10)
	s_nop 0
	v_lshlrev_b32_e32 v8, 16, v4
	v_and_b32_e32 v9, 0xffff0000, v4
	v_lshlrev_b32_e32 v4, 16, v5
	v_and_b32_e32 v5, 0xffff0000, v5
	s_waitcnt vmcnt(9)
	v_pk_fma_f32 v[10:11], v[14:15], v[46:47], v[4:5] op_sel_hi:[1,0,1]
	v_lshlrev_b32_e32 v4, 16, v6
	v_and_b32_e32 v5, 0xffff0000, v6
	v_lshlrev_b32_e32 v6, 16, v7
	v_and_b32_e32 v7, 0xffff0000, v7
	v_pk_fma_f32 v[8:9], v[12:13], v[46:47], v[8:9] op_sel_hi:[1,0,1]
	v_pk_fma_f32 v[12:13], v[16:17], v[46:47], v[6:7] op_sel_hi:[1,0,1]
	v_pk_fma_f32 v[14:15], v[18:19], v[46:47], v[4:5] op_sel_hi:[1,0,1]
	v_lshlrev_b32_e32 v16, 14, v48
	v_mov_b32_e32 v17, v184
	v_cvt_pk_bf16_f32 v4, v8, v9
	v_cvt_pk_bf16_f32 v5, v10, v11
	v_cvt_pk_bf16_f32 v6, v14, v15
	v_cvt_pk_bf16_f32 v7, v12, v13
	v_lshl_add_u64 v[16:17], v[32:33], 0, v[16:17]
	global_store_dwordx4 v[16:17], v[4:7], off
	s_waitcnt vmcnt(9)
	s_nop 0
	v_lshlrev_b32_e32 v4, 16, v0
	v_and_b32_e32 v5, 0xffff0000, v0
	v_lshlrev_b32_e32 v0, 16, v1
	v_and_b32_e32 v1, 0xffff0000, v1
	s_waitcnt vmcnt(8)
	v_pk_fma_f32 v[38:39], v[10:11], v[44:45], v[0:1] op_sel_hi:[1,0,1]
	v_lshlrev_b32_e32 v0, 16, v2
	v_and_b32_e32 v1, 0xffff0000, v2
	v_lshlrev_b32_e32 v2, 16, v3
	v_and_b32_e32 v3, 0xffff0000, v3
	v_pk_fma_f32 v[36:37], v[8:9], v[44:45], v[4:5] op_sel_hi:[1,0,1]
	v_pk_fma_f32 v[42:43], v[12:13], v[44:45], v[2:3] op_sel_hi:[1,0,1]
	v_pk_fma_f32 v[40:41], v[14:15], v[44:45], v[0:1] op_sel_hi:[1,0,1]
	s_cbranch_scc0 .LBB0_163
	v_add_u32_e32 v45, s10, v45
	v_cmp_lt_i32_e32 vcc, s55, v45
	s_or_b64 s[38:39], vcc, s[38:39]
	s_andn2_b64 exec, exec, s[38:39]
	s_cbranch_execnz .LBB0_162
